# conv main sweep loops: 12 per-iteration address v_add replaced by one loop-carried base register + ds_read2_b32 immediate offsets
# speedup vs baseline: 1.0065x; 1.0065x over previous
; template <int NQ, int NB, int L>
; __device__ __forceinline__ void conv_unit(LAS unsigned char* lds, const Args& a, int j, int seq0, int c, int tid) {
;     ...
;         const int dl_a = mw + 3 * GS - S_HI, dl_b = mw - S_LO;
;         static_assert(((3 * GS / 32) % 2 == 0) && (((S_HI - S_LO - 3 * GS) / 32 + 1) % 2 == 1), "conv step-count parity");
; #pragma unroll 1
;         for (int dl = d_lo; dl < dl_a; dl += 64) { CONV_STEP(Bc, Bn, dl, true); CONV_STEP(Bn, Bc, dl + 32, true); }
; #pragma unroll 1
;         for (int dl = dl_a; dl < dl_b; dl += 64) { CONV_STEP(Bc, Bn, dl, false); CONV_STEP(Bn, Bc, dl + 32, false); }
;         CONV_STEP(Bc, Bn, dl_b, false);
; #pragma unroll 1
;         for (int dl = dl_b + 32; dl <= d_hi; dl += 64) { CONV_STEP(Bn, Bc, dl, true); CONV_STEP(Bc, Bn, dl + 32, true); }
.LBB0_1340:
	v_mov_b32_e32 v114, 0
	v_mov_b32_e32 v32, v199
	v_add_u32_e32 v205, v199, v194
	v_add_u32_e32 v205, 0x16ffe, v205
	s_mov_b32 s94, s91
	v_mov_b32_e32 v115, v114
	v_mov_b32_e32 v116, v114
	v_mov_b32_e32 v117, v114
	v_mov_b32_e32 v118, v114
	v_mov_b32_e32 v119, v114
	v_mov_b32_e32 v120, v114
	v_mov_b32_e32 v121, v114
	v_mov_b32_e32 v122, v114
	v_mov_b32_e32 v123, v114
	v_mov_b32_e32 v124, v114
	v_mov_b32_e32 v125, v114
	v_mov_b32_e32 v126, v114
	v_mov_b32_e32 v127, v114
	v_mov_b32_e32 v128, v114
	v_mov_b32_e32 v129, v114
.LBB0_1341:
	s_waitcnt lgkmcnt(3)
	v_mfma_f32_16x16x32_bf16 v[60:63], v[70:73], v[82:85], v[90:93]
	v_add_u32_e32 v136, v134, v194
	s_mov_b32 s56, s71
	v_mfma_f32_16x16x32_bf16 v[64:67], v[74:77], v[82:85], v[86:89]
	s_waitcnt lgkmcnt(1)
	v_mfma_f32_16x16x32_bf16 v[34:37], v[78:81], v[24:27], v[36:39]
	v_mfma_f32_16x16x32_bf16 v[52:55], v[16:19], v[82:85], v[52:55]
	v_mfma_f32_16x16x32_bf16 v[56:59], v[78:81], v[82:85], v[94:97]
	v_mfma_f32_16x16x32_bf16 v[40:43], v[16:19], v[106:109], v[40:43]
	v_mfma_f32_16x16x32_bf16 v[28:31], v[78:81], v[106:109], v[28:31]
	v_mfma_f32_16x16x32_bf16 v[44:47], v[70:73], v[106:109], v[44:47]
	v_mfma_f32_16x16x32_bf16 v[48:51], v[74:77], v[106:109], v[48:51]
	ds_read_b128 v[82:85], v136 offset:8576
	ds_read_b128 v[106:109], v136 offset:8832
	ds_read_b128 v[130:133], v136 offset:9088
	ds_read_b128 v[148:151], v136 offset:9344
	v_mfma_f32_16x16x32_bf16 v[20:23], v[16:19], v[24:27], v[20:23]
	v_mfma_f32_16x16x32_bf16 v[102:105], v[70:73], v[24:27], v[102:105]
	v_mfma_f32_16x16x32_bf16 v[98:101], v[74:77], v[24:27], v[98:101]
	s_waitcnt lgkmcnt(4)
	v_mfma_f32_16x16x32_bf16 v[24:27], v[16:19], v[110:113], v[114:117]
	ds_read2_b32 v[16:17], v205 offset0:24 offset1:25
	ds_read2_b32 v[68:69], v205 offset0:25 offset1:26
	ds_read2_b32 v[18:19], v205 offset0:27 offset1:28
	ds_read2_b32 v[86:87], v205 offset0:16 offset1:17
	ds_read2_b32 v[88:89], v205 offset0:17 offset1:18
	ds_read2_b32 v[90:91], v205 offset0:19 offset1:20
	v_mfma_f32_16x16x32_bf16 v[78:81], v[78:81], v[110:113], v[118:121]
	v_mfma_f32_16x16x32_bf16 v[122:125], v[70:73], v[110:113], v[122:125]
	v_mfma_f32_16x16x32_bf16 v[126:129], v[74:77], v[110:113], v[126:129]
	s_waitcnt lgkmcnt(3)
	v_alignbit_b32 v19, v19, v18, v15
	v_alignbit_b32 v18, v18, v69, v14
	v_alignbit_b32 v17, v69, v17, v13
	v_alignbit_b32 v16, v68, v16, v12
	v_mfma_f32_16x16x32_bf16 v[118:121], v[74:77], v[148:151], v[78:81]
	s_waitcnt lgkmcnt(0)
	s_nop 1
	v_alignbit_b32 v81, v91, v90, v15
	v_alignbit_b32 v80, v90, v89, v14
	v_alignbit_b32 v79, v89, v87, v13
	v_alignbit_b32 v78, v88, v86, v12
	v_mfma_f32_16x16x32_bf16 v[94:97], v[74:77], v[82:85], v[56:59]
	v_mfma_f32_16x16x32_bf16 v[36:39], v[74:77], v[130:133], v[34:37]
	s_nop 1
	v_mfma_f32_16x16x32_bf16 v[90:93], v[16:19], v[82:85], v[60:63]
	v_mfma_f32_16x16x32_bf16 v[86:89], v[78:81], v[82:85], v[64:67]
	s_nop 0
	v_mfma_f32_16x16x32_bf16 v[52:55], v[70:73], v[82:85], v[52:55]
	ds_read_b128 v[82:85], v136 offset:8512
	v_mfma_f32_16x16x32_bf16 v[40:43], v[70:73], v[106:109], v[40:43]
	v_mfma_f32_16x16x32_bf16 v[28:31], v[74:77], v[106:109], v[28:31]
	v_mfma_f32_16x16x32_bf16 v[114:117], v[70:73], v[148:151], v[24:27]
	v_mfma_f32_16x16x32_bf16 v[44:47], v[16:19], v[106:109], v[44:47]
	v_mfma_f32_16x16x32_bf16 v[48:51], v[78:81], v[106:109], v[48:51]
	ds_read_b128 v[106:109], v136 offset:8768
	ds_read_b128 v[24:27], v136 offset:9024
	ds_read_b128 v[110:113], v136 offset:9280
	ds_read2_b32 v[34:35], v205 offset0:8 offset1:9
	ds_read2_b32 v[56:57], v205 offset0:9 offset1:10
	ds_read2_b32 v[58:59], v205 offset0:11 offset1:12
	ds_read2_b32 v[60:61], v205 offset0:0 offset1:1
	ds_read2_b32 v[62:63], v205 offset0:1 offset1:2
	ds_read2_b32 v[64:65], v205 offset0:3 offset1:4
	v_mfma_f32_16x16x32_bf16 v[20:23], v[70:73], v[130:133], v[20:23]
	s_waitcnt lgkmcnt(4)
	v_alignbit_b32 v71, v57, v35, v13
	s_waitcnt lgkmcnt(3)
	v_alignbit_b32 v73, v59, v58, v15
	v_mfma_f32_16x16x32_bf16 v[102:105], v[16:19], v[130:133], v[102:105]
	v_alignbit_b32 v72, v58, v57, v14
	v_alignbit_b32 v70, v56, v34, v12
	v_mfma_f32_16x16x32_bf16 v[98:101], v[78:81], v[130:133], v[98:101]
	v_mfma_f32_16x16x32_bf16 v[122:125], v[16:19], v[148:151], v[122:125]
	v_mfma_f32_16x16x32_bf16 v[126:129], v[78:81], v[148:151], v[126:129]
	s_add_i32 s94, s94, 64
	s_addk_i32 s71, 0xff80
	s_waitcnt lgkmcnt(0)
	v_alignbit_b32 v77, v65, v64, v15
	v_alignbit_b32 v76, v64, v63, v14
	v_alignbit_b32 v75, v63, v61, v13
	v_alignbit_b32 v74, v62, v60, v12
	v_add_u32_e32 v134, 0xffffff80, v134
	s_cmp_gt_i32 s94, s50
	v_add_u32_e32 v205, 0xffffff80, v205
	v_add_u32_e32 v32, 0xffffff80, v32
	s_cbranch_scc0 .LBB0_1341
	v_mfma_f32_16x16x32_bf16 v[66:69], v[16:19], v[82:85], v[52:55]
	v_add_u32_e32 v32, s75, v193
	v_mfma_f32_16x16x32_bf16 v[54:57], v[70:73], v[106:109], v[44:47]
	v_mfma_f32_16x16x32_bf16 v[50:53], v[74:77], v[106:109], v[48:51]
	v_mfma_f32_16x16x32_bf16 v[46:49], v[16:19], v[24:27], v[20:23]
	s_nop 2
	v_add_u32_e32 v20, v134, v194
	v_add_u32_e32 v21, s83, v193
	v_mfma_f32_16x16x32_bf16 v[62:65], v[16:19], v[106:109], v[40:43]
	v_mfma_f32_16x16x32_bf16 v[58:61], v[78:81], v[106:109], v[28:31]
	v_mfma_f32_16x16x32_bf16 v[42:45], v[78:81], v[24:27], v[36:39]
	v_mfma_f32_16x16x32_bf16 v[34:37], v[70:73], v[24:27], v[102:105]
	v_mfma_f32_16x16x32_bf16 v[24:27], v[74:77], v[24:27], v[98:101]
	ds_read_b128 v[130:133], v20 offset:8832
	s_nop 1
	ds_read_b128 v[98:101], v20 offset:9088
	v_mfma_f32_16x16x32_bf16 v[38:41], v[16:19], v[110:113], v[114:117]
	ds_read2_b32 v[16:17], v21 offset0:1 offset1:2
	ds_read2_b32 v[18:19], v21 offset0:3 offset1:4
	ds_read2_b32 v[106:107], v32 offset1:1
	ds_read2_b32 v[102:103], v21 offset1:1
	ds_read_b128 v[114:117], v20 offset:9344
	s_waitcnt lgkmcnt(3)
	v_alignbit_b32 v105, v19, v18, v15
	v_mfma_f32_16x16x32_bf16 v[28:31], v[78:81], v[110:113], v[118:121]
	s_nop 2
	ds_read2_b32 v[118:119], v32 offset0:1 offset1:2
	ds_read2_b32 v[108:109], v32 offset0:3 offset1:4
	v_alignbit_b32 v104, v18, v17, v14
	s_waitcnt lgkmcnt(3)
	v_alignbit_b32 v103, v17, v103, v13
	v_mfma_f32_16x16x32_bf16 v[20:23], v[70:73], v[110:113], v[122:125]
	v_alignbit_b32 v102, v16, v102, v12
	v_mfma_f32_16x16x32_bf16 v[16:19], v[74:77], v[110:113], v[126:129]
	s_waitcnt lgkmcnt(0)
	v_alignbit_b32 v109, v109, v108, v15
	v_alignbit_b32 v108, v108, v119, v14
	v_alignbit_b32 v107, v119, v107, v13
	v_alignbit_b32 v106, v118, v106, v12
	v_mov_b64_e32 v[112:113], v[72:73]
	v_mov_b64_e32 v[120:121], v[76:77]
	s_movk_i32 s71, 0xc0
	v_mov_b32_e32 v32, v216
	s_mov_b32 s94, s92
	v_mov_b64_e32 v[110:111], v[70:71]
	v_mov_b64_e32 v[118:119], v[74:75]
	s_branch .LBB0_1344

; template <int NQ, int NB, int L>
; __device__ __forceinline__ void conv_unit(LAS unsigned char* lds, const Args& a, int j, int seq0, int c, int tid) {
;     ...
;         const int dl_a = mw + 3 * GS - S_HI, dl_b = mw - S_LO;
;         static_assert(((3 * GS / 32) % 2 == 0) && (((S_HI - S_LO - 3 * GS) / 32 + 1) % 2 == 1), "conv step-count parity");
; #pragma unroll 1
;         for (int dl = d_lo; dl < dl_a; dl += 64) { CONV_STEP(Bc, Bn, dl, true); CONV_STEP(Bn, Bc, dl + 32, true); }
; #pragma unroll 1
;         for (int dl = dl_a; dl < dl_b; dl += 64) { CONV_STEP(Bc, Bn, dl, false); CONV_STEP(Bn, Bc, dl + 32, false); }
;         CONV_STEP(Bc, Bn, dl_b, false);
; #pragma unroll 1
;         for (int dl = dl_b + 32; dl <= d_hi; dl += 64) { CONV_STEP(Bn, Bc, dl, true); CONV_STEP(Bc, Bn, dl + 32, true); }
.LBB0_1545:
	v_mov_b32_e32 v122, 0
	v_mov_b32_e32 v32, v222
	v_add_u32_e32 v205, v222, v217
	v_add_u32_e32 v205, 0x1acfe, v205
	s_mov_b32 vcc_lo, s86
	v_mov_b32_e32 v123, v122
	v_mov_b32_e32 v124, v122
	v_mov_b32_e32 v125, v122
	v_mov_b32_e32 v126, v122
	v_mov_b32_e32 v127, v122
	v_mov_b32_e32 v128, v122
	v_mov_b32_e32 v129, v122
	v_mov_b32_e32 v130, v122
	v_mov_b32_e32 v131, v122
	v_mov_b32_e32 v132, v122
	v_mov_b32_e32 v133, v122
	v_mov_b32_e32 v134, v122
	v_mov_b32_e32 v135, v122
	v_mov_b32_e32 v136, v122
	v_mov_b32_e32 v137, v122
.LBB0_1546:
	s_waitcnt lgkmcnt(3)
	v_mfma_f32_16x16x32_bf16 v[68:71], v[78:81], v[90:93], v[94:97]
	v_add_u32_e32 v144, v142, v217
	s_waitcnt lgkmcnt(1)
	v_mfma_f32_16x16x32_bf16 v[28:31], v[24:27], v[36:39], v[28:31]
	v_mfma_f32_16x16x32_bf16 v[44:47], v[86:89], v[36:39], v[44:47]
	s_mov_b32 s49, s56
	v_mfma_f32_16x16x32_bf16 v[110:113], v[78:81], v[36:39], v[110:113]
	v_mfma_f32_16x16x32_bf16 v[106:109], v[82:85], v[36:39], v[106:109]
	v_mfma_f32_16x16x32_bf16 v[60:63], v[24:27], v[90:93], v[60:63]
	v_mfma_f32_16x16x32_bf16 v[64:67], v[86:89], v[90:93], v[102:105]
	v_mfma_f32_16x16x32_bf16 v[72:75], v[82:85], v[90:93], v[98:101]
	v_mfma_f32_16x16x32_bf16 v[48:51], v[24:27], v[114:117], v[48:51]
	v_mfma_f32_16x16x32_bf16 v[40:43], v[86:89], v[114:117], v[40:43]
	v_mfma_f32_16x16x32_bf16 v[52:55], v[78:81], v[114:117], v[52:55]
	v_mfma_f32_16x16x32_bf16 v[56:59], v[82:85], v[114:117], v[56:59]
	ds_read_b128 v[90:93], v144 offset:16768
	ds_read_b128 v[114:117], v144 offset:17280
	ds_read_b128 v[138:141], v144 offset:17792
	ds_read_b128 v[178:181], v144 offset:18304
	s_waitcnt lgkmcnt(4)
	v_mfma_f32_16x16x32_bf16 v[34:37], v[24:27], v[118:121], v[122:125]
	ds_read2_b32 v[24:25], v205 offset0:24 offset1:25
	ds_read2_b32 v[38:39], v205 offset0:25 offset1:26
	ds_read2_b32 v[26:27], v205 offset0:27 offset1:28
	ds_read2_b32 v[76:77], v205 offset0:16 offset1:17
	ds_read2_b32 v[98:99], v205 offset0:17 offset1:18
	ds_read2_b32 v[94:95], v205 offset0:19 offset1:20
	v_mfma_f32_16x16x32_bf16 v[86:89], v[86:89], v[118:121], v[126:129]
	v_mfma_f32_16x16x32_bf16 v[130:133], v[78:81], v[118:121], v[130:133]
	v_mfma_f32_16x16x32_bf16 v[134:137], v[82:85], v[118:121], v[134:137]
	s_waitcnt lgkmcnt(3)
	v_alignbit_b32 v27, v27, v26, v23
	v_alignbit_b32 v26, v26, v39, v22
	v_alignbit_b32 v25, v39, v25, v21
	v_alignbit_b32 v24, v38, v24, v20
	v_mfma_f32_16x16x32_bf16 v[126:129], v[82:85], v[178:181], v[86:89]
	s_waitcnt lgkmcnt(0)
	s_nop 1
	v_alignbit_b32 v89, v95, v94, v23
	v_alignbit_b32 v88, v94, v99, v22
	v_alignbit_b32 v87, v99, v77, v21
	v_alignbit_b32 v86, v98, v76, v20
	v_mfma_f32_16x16x32_bf16 v[102:105], v[82:85], v[90:93], v[64:67]
	v_mfma_f32_16x16x32_bf16 v[122:125], v[78:81], v[178:181], v[34:37]
	s_nop 1
	v_mfma_f32_16x16x32_bf16 v[94:97], v[24:27], v[90:93], v[68:71]
	v_mfma_f32_16x16x32_bf16 v[98:101], v[86:89], v[90:93], v[72:75]
	s_nop 0
	v_mfma_f32_16x16x32_bf16 v[60:63], v[78:81], v[90:93], v[60:63]
	ds_read_b128 v[90:93], v144 offset:16704
	v_mfma_f32_16x16x32_bf16 v[48:51], v[78:81], v[114:117], v[48:51]
	v_mfma_f32_16x16x32_bf16 v[40:43], v[82:85], v[114:117], v[40:43]
	v_mfma_f32_16x16x32_bf16 v[52:55], v[24:27], v[114:117], v[52:55]
	v_mfma_f32_16x16x32_bf16 v[56:59], v[86:89], v[114:117], v[56:59]
	ds_read_b128 v[114:117], v144 offset:17216
	ds_read_b128 v[36:39], v144 offset:17728
	ds_read_b128 v[118:121], v144 offset:18240
	ds_read2_b32 v[34:35], v205 offset0:8 offset1:9
	ds_read2_b32 v[64:65], v205 offset0:9 offset1:10
	ds_read2_b32 v[66:67], v205 offset0:11 offset1:12
	ds_read2_b32 v[68:69], v205 offset0:0 offset1:1
	ds_read2_b32 v[70:71], v205 offset0:1 offset1:2
	ds_read2_b32 v[72:73], v205 offset0:3 offset1:4
	v_mfma_f32_16x16x32_bf16 v[28:31], v[78:81], v[138:141], v[28:31]
	s_waitcnt lgkmcnt(4)
	v_alignbit_b32 v79, v65, v35, v21
	s_waitcnt lgkmcnt(3)
	v_alignbit_b32 v81, v67, v66, v23
	v_mfma_f32_16x16x32_bf16 v[44:47], v[82:85], v[138:141], v[44:47]
	v_alignbit_b32 v80, v66, v65, v22
	v_alignbit_b32 v78, v64, v34, v20
	v_mfma_f32_16x16x32_bf16 v[110:113], v[24:27], v[138:141], v[110:113]
	v_mfma_f32_16x16x32_bf16 v[106:109], v[86:89], v[138:141], v[106:109]
	v_mfma_f32_16x16x32_bf16 v[130:133], v[24:27], v[178:181], v[130:133]
	v_mfma_f32_16x16x32_bf16 v[134:137], v[86:89], v[178:181], v[134:137]
	s_add_i32 vcc_lo, vcc_lo, 64
	s_addk_i32 s56, 0xff80
	s_waitcnt lgkmcnt(0)
	v_alignbit_b32 v85, v73, v72, v23
	v_alignbit_b32 v84, v72, v71, v22
	v_alignbit_b32 v83, v71, v69, v21
	v_alignbit_b32 v82, v70, v68, v20
	v_add_u32_e32 v142, 0xffffff80, v142
	s_cmp_ge_i32 vcc_lo, s51
	v_add_u32_e32 v205, 0xffffff80, v205
	v_add_u32_e32 v32, 0xffffff80, v32
	s_cbranch_scc0 .LBB0_1546
	v_mfma_f32_16x16x32_bf16 v[74:77], v[24:27], v[90:93], v[60:63]
	v_add_u32_e32 v32, s97, v216
	v_mfma_f32_16x16x32_bf16 v[62:65], v[78:81], v[114:117], v[52:55]
	v_mfma_f32_16x16x32_bf16 v[58:61], v[82:85], v[114:117], v[56:59]
	v_mfma_f32_16x16x32_bf16 v[54:57], v[24:27], v[36:39], v[28:31]
	s_nop 2
	v_add_u32_e32 v28, v142, v217
	v_add_u32_e32 v29, s50, v216
	v_mfma_f32_16x16x32_bf16 v[70:73], v[24:27], v[114:117], v[48:51]
	v_mfma_f32_16x16x32_bf16 v[66:69], v[86:89], v[114:117], v[40:43]
	v_mfma_f32_16x16x32_bf16 v[50:53], v[86:89], v[36:39], v[44:47]
	v_mfma_f32_16x16x32_bf16 v[42:45], v[78:81], v[36:39], v[110:113]
	v_mfma_f32_16x16x32_bf16 v[34:37], v[82:85], v[36:39], v[106:109]
	ds_read_b128 v[138:141], v28 offset:17280
	s_nop 1
	ds_read_b128 v[106:109], v28 offset:17792
	v_mfma_f32_16x16x32_bf16 v[46:49], v[24:27], v[118:121], v[122:125]
	ds_read2_b32 v[24:25], v29 offset0:1 offset1:2
	ds_read2_b32 v[26:27], v29 offset0:3 offset1:4
	ds_read2_b32 v[114:115], v32 offset1:1
	ds_read2_b32 v[110:111], v29 offset1:1
	ds_read_b128 v[122:125], v28 offset:18304
	s_waitcnt lgkmcnt(3)
	v_alignbit_b32 v113, v27, v26, v23
	v_mfma_f32_16x16x32_bf16 v[38:41], v[86:89], v[118:121], v[126:129]
	s_nop 2
	ds_read2_b32 v[126:127], v32 offset0:1 offset1:2
	ds_read2_b32 v[116:117], v32 offset0:3 offset1:4
	v_alignbit_b32 v112, v26, v25, v22
	s_waitcnt lgkmcnt(3)
	v_alignbit_b32 v111, v25, v111, v21
	v_mfma_f32_16x16x32_bf16 v[28:31], v[78:81], v[118:121], v[130:133]
	v_alignbit_b32 v110, v24, v110, v20
	v_mfma_f32_16x16x32_bf16 v[24:27], v[82:85], v[118:121], v[134:137]
	s_waitcnt lgkmcnt(0)
	v_alignbit_b32 v117, v117, v116, v23
	v_alignbit_b32 v116, v116, v127, v22
	v_alignbit_b32 v115, v127, v115, v21
	v_alignbit_b32 v114, v126, v114, v20
	v_mov_b64_e32 v[120:121], v[80:81]
	v_mov_b64_e32 v[128:129], v[84:85]
	s_movk_i32 s56, 0x1c0
	v_mov_b32_e32 v32, v225
	s_mov_b32 vcc_lo, s91
	v_mov_b64_e32 v[118:119], v[78:79]
	v_mov_b64_e32 v[126:127], v[82:83]
	s_branch .LBB0_1549
